# code placement: GU epilogue start at a 64-byte boundary + 4 bytes
# baseline (speedup 1.0000x reference)
; #define LAS __attribute__((address_space(3)))
; #define BAR() { __builtin_amdgcn_sched_barrier(0); __builtin_amdgcn_s_barrier(); asm volatile("" ::: "memory"); __builtin_amdgcn_sched_barrier(0); }
; DI void gemm_stream2(const bf16_t* __restrict__ A, int lda, const bf16_t* __restrict__ Bt, int ldb, int K, int m0, int n0, ...
;     ...
; #pragma unroll
;         for (int ks = 0; ks < 2; ++ks) {
;             const unsigned fo = ks ? fo1 : fo0;
;             bf16x8 af[4], bfr[4];
; #pragma unroll
;             for (int i = 0; i < 4; ++i) { af[i] = *(const LAS bf16x8*)(base + aoff + i * 2048 + fo); bfr[i] = *(const LAS bf16x8*)(base + boff + i * 2048 + fo); }
;             if (ks == 1 && more) { if (pf) asm volatile("s_waitcnt vmcnt(3)" ::: "memory"); else asm volatile("s_waitcnt vmcnt(0)" ::: "memory"); }
;             if (pf) { PIECE(s2, ks * 3 + 0); PIECE(s2, ks * 3 + 1); PIECE(s2, ks * 3 + 2); }
;             asm volatile("s_waitcnt lgkmcnt(0)" ::: "memory");
;             BAR();
;             __builtin_amdgcn_s_setprio(1);
; #pragma unroll
;             for (int mi = 0; mi < 4; ++mi)
; #pragma unroll
;                 for (int ni = 0; ni < 4; ++ni) acc[mi][ni] = __builtin_amdgcn_mfma_f32_16x16x32_bf16(bfr[ni], af[mi], acc[mi][ni], 0, 0, 0);
;             __builtin_amdgcn_s_setprio(0);
;             BAR();
;         }
.Lgu_nosw2:
	s_add_i32 m0, s39, 0x4000
	s_nop 0
	global_load_lds_dwordx4 v184, s[68:69]
	s_add_i32 m0, s39, 0x4400
	s_nop 0
	global_load_lds_dwordx4 v185, s[68:69]
	s_add_u32 s68, s68, 0x80
	s_addc_u32 s69, s69, 0
	s_waitcnt lgkmcnt(0)
	s_waitcnt vmcnt(8)
	s_barrier
	s_setprio 1
	v_mfma_f32_16x16x32_bf16 v[24:27], v[0:3], v[152:155], v[24:27]
	v_mfma_f32_16x16x32_bf16 v[28:31], v[8:11], v[152:155], v[28:31]
	v_mfma_f32_16x16x32_bf16 v[32:35], v[0:3], v[160:163], v[32:35]
	v_mfma_f32_16x16x32_bf16 v[36:39], v[8:11], v[160:163], v[36:39]
	v_mfma_f32_16x16x32_bf16 v[40:43], v[0:3], v[168:171], v[40:43]
	v_mfma_f32_16x16x32_bf16 v[44:47], v[8:11], v[168:171], v[44:47]
	v_mfma_f32_16x16x32_bf16 v[48:51], v[0:3], v[176:179], v[48:51]
	v_mfma_f32_16x16x32_bf16 v[52:55], v[8:11], v[176:179], v[52:55]
	v_mfma_f32_16x16x32_bf16 v[24:27], v[4:7], v[156:159], v[24:27]
	v_mfma_f32_16x16x32_bf16 v[28:31], v[12:15], v[156:159], v[28:31]
	v_mfma_f32_16x16x32_bf16 v[32:35], v[4:7], v[164:167], v[32:35]
	v_mfma_f32_16x16x32_bf16 v[36:39], v[12:15], v[164:167], v[36:39]
	v_mfma_f32_16x16x32_bf16 v[40:43], v[4:7], v[172:175], v[40:43]
	v_mfma_f32_16x16x32_bf16 v[44:47], v[12:15], v[172:175], v[44:47]
	v_mfma_f32_16x16x32_bf16 v[48:51], v[4:7], v[180:183], v[48:51]
	v_mfma_f32_16x16x32_bf16 v[52:55], v[12:15], v[180:183], v[52:55]
	v_mfma_f32_16x16x32_bf16 v[56:59], v[196:199], v[152:155], v[56:59]
	v_mfma_f32_16x16x32_bf16 v[60:63], v[204:207], v[152:155], v[60:63]
	v_mfma_f32_16x16x32_bf16 v[64:67], v[196:199], v[160:163], v[64:67]
	v_mfma_f32_16x16x32_bf16 v[68:71], v[204:207], v[160:163], v[68:71]
	v_mfma_f32_16x16x32_bf16 v[72:75], v[196:199], v[168:171], v[72:75]
	v_mfma_f32_16x16x32_bf16 v[76:79], v[204:207], v[168:171], v[76:79]
	v_mfma_f32_16x16x32_bf16 v[80:83], v[196:199], v[176:179], v[80:83]
	v_mfma_f32_16x16x32_bf16 v[84:87], v[204:207], v[176:179], v[84:87]
	v_mfma_f32_16x16x32_bf16 v[56:59], v[200:203], v[156:159], v[56:59]
	v_mfma_f32_16x16x32_bf16 v[60:63], v[208:211], v[156:159], v[60:63]
	v_mfma_f32_16x16x32_bf16 v[64:67], v[200:203], v[164:167], v[64:67]
	v_mfma_f32_16x16x32_bf16 v[68:71], v[208:211], v[164:167], v[68:71]
	v_mfma_f32_16x16x32_bf16 v[72:75], v[200:203], v[172:175], v[72:75]
	v_mfma_f32_16x16x32_bf16 v[76:79], v[208:211], v[172:175], v[76:79]
	v_mfma_f32_16x16x32_bf16 v[80:83], v[200:203], v[180:183], v[80:83]
	v_mfma_f32_16x16x32_bf16 v[84:87], v[208:211], v[180:183], v[84:87]
	s_setprio 0
	s_barrier
	ds_read_b128 v[152:155], v186 offset:49168
	ds_read_b128 v[156:159], v187 offset:49168
	ds_read_b128 v[160:163], v186 offset:51216
	ds_read_b128 v[164:167], v187 offset:51216
	ds_read_b128 v[168:171], v186 offset:53264
	ds_read_b128 v[172:175], v187 offset:53264
	ds_read_b128 v[176:179], v186 offset:55312
	ds_read_b128 v[180:183], v187 offset:55312
	s_add_i32 m0, s39, 0x18000
	s_nop 0
	global_load_lds_dwordx4 v184, s[70:71]
	s_add_i32 m0, s39, 0x18400
	s_nop 0
	global_load_lds_dwordx4 v185, s[70:71]
	s_add_u32 s70, s70, 0x80
	s_addc_u32 s71, s71, 0
	s_add_i32 m0, s39, 0x8000
	s_nop 0
	global_load_lds_dwordx4 v184, s[66:67]
	s_add_i32 m0, s39, 0x8400
	s_nop 0
	global_load_lds_dwordx4 v185, s[66:67]
	s_add_u32 s66, s66, 0x80
	s_addc_u32 s67, s67, 0
	s_add_i32 m0, s39, 0x1c000
	s_nop 0
	global_load_lds_dwordx4 v184, s[72:73]
	s_add_i32 m0, s39, 0x1c400
	s_nop 0
	global_load_lds_dwordx4 v185, s[72:73]
	s_add_u32 s72, s72, 0x80
	s_addc_u32 s73, s73, 0
	s_waitcnt lgkmcnt(0)
	s_waitcnt vmcnt(8)
	s_barrier
	s_setprio 1
	v_mfma_f32_16x16x32_bf16 v[88:91], v[0:3], v[152:155], v[88:91]
	v_mfma_f32_16x16x32_bf16 v[92:95], v[8:11], v[152:155], v[92:95]
	v_mfma_f32_16x16x32_bf16 v[96:99], v[0:3], v[160:163], v[96:99]
	v_mfma_f32_16x16x32_bf16 v[100:103], v[8:11], v[160:163], v[100:103]
	v_mfma_f32_16x16x32_bf16 v[104:107], v[0:3], v[168:171], v[104:107]
	v_mfma_f32_16x16x32_bf16 v[108:111], v[8:11], v[168:171], v[108:111]
	v_mfma_f32_16x16x32_bf16 v[112:115], v[0:3], v[176:179], v[112:115]
	v_mfma_f32_16x16x32_bf16 v[116:119], v[8:11], v[176:179], v[116:119]
	v_mfma_f32_16x16x32_bf16 v[88:91], v[4:7], v[156:159], v[88:91]
	v_mfma_f32_16x16x32_bf16 v[92:95], v[12:15], v[156:159], v[92:95]
	v_mfma_f32_16x16x32_bf16 v[96:99], v[4:7], v[164:167], v[96:99]
	v_mfma_f32_16x16x32_bf16 v[100:103], v[12:15], v[164:167], v[100:103]
	v_mfma_f32_16x16x32_bf16 v[104:107], v[4:7], v[172:175], v[104:107]
	v_mfma_f32_16x16x32_bf16 v[108:111], v[12:15], v[172:175], v[108:111]
	v_mfma_f32_16x16x32_bf16 v[112:115], v[4:7], v[180:183], v[112:115]
	v_mfma_f32_16x16x32_bf16 v[116:119], v[12:15], v[180:183], v[116:119]
	v_mfma_f32_16x16x32_bf16 v[120:123], v[196:199], v[152:155], v[120:123]
	v_mfma_f32_16x16x32_bf16 v[124:127], v[204:207], v[152:155], v[124:127]
	v_mfma_f32_16x16x32_bf16 v[128:131], v[196:199], v[160:163], v[128:131]
	v_mfma_f32_16x16x32_bf16 v[132:135], v[204:207], v[160:163], v[132:135]
	v_mfma_f32_16x16x32_bf16 v[136:139], v[196:199], v[168:171], v[136:139]
	v_mfma_f32_16x16x32_bf16 v[140:143], v[204:207], v[168:171], v[140:143]
	v_mfma_f32_16x16x32_bf16 v[144:147], v[196:199], v[176:179], v[144:147]
	v_mfma_f32_16x16x32_bf16 v[148:151], v[204:207], v[176:179], v[148:151]
	v_mfma_f32_16x16x32_bf16 v[120:123], v[200:203], v[156:159], v[120:123]
	v_mfma_f32_16x16x32_bf16 v[124:127], v[208:211], v[156:159], v[124:127]
	v_mfma_f32_16x16x32_bf16 v[128:131], v[200:203], v[164:167], v[128:131]
	v_mfma_f32_16x16x32_bf16 v[132:135], v[208:211], v[164:167], v[132:135]
	v_mfma_f32_16x16x32_bf16 v[136:139], v[200:203], v[172:175], v[136:139]
	v_mfma_f32_16x16x32_bf16 v[140:143], v[208:211], v[172:175], v[140:143]
	v_mfma_f32_16x16x32_bf16 v[144:147], v[200:203], v[180:183], v[144:147]
	v_mfma_f32_16x16x32_bf16 v[148:151], v[208:211], v[180:183], v[148:151]
	s_setprio 0
	s_barrier
; #define LAS __attribute__((address_space(3)))
; #define BAR() { __builtin_amdgcn_sched_barrier(0); __builtin_amdgcn_s_barrier(); asm volatile("" ::: "memory"); __builtin_amdgcn_sched_barrier(0); }
; DI void gemm_stream2(const bf16_t* __restrict__ A, int lda, const bf16_t* __restrict__ Bt, int ldb, int K, int m0, int n0, ...
;     ...
;     for (int kt = 0; kt < nk; ++kt) {
;         const bool pf = (kt + 2 < nk) || has_next, more = (kt + 1 < nk) || has_next;
;         const bf16_t* pa = (kt + 2 < nk) ? ga + (kt + 2) * 64 : gan + (kt + 2 - nk) * 64;
;         const bf16_t* pb = (kt + 2 < nk) ? gb + (kt + 2) * 64 : gbn + (kt + 2 - nk) * 64;
;         const int plda = (kt + 2 < nk) ? lda : ldan, pldb = (kt + 2 < nk) ? ldb : ldbn;
;         const int s2 = st >= 1 ? st - 1 : 2;
;         const LAS char* base = lds + st * 49152;
; #pragma unroll
;         for (int ks = 0; ks < 2; ++ks) {
;             const unsigned fo = ks ? fo1 : fo0;
;             bf16x8 af[4], bfr[4];
; #pragma unroll
;             for (int i = 0; i < 4; ++i) { af[i] = *(const LAS bf16x8*)(base + aoff + i * 2048 + fo); bfr[i] = *(const LAS bf16x8*)(base + boff + i * 2048 + fo); }
;             if (ks == 1 && more) { if (pf) asm volatile("s_waitcnt vmcnt(3)" ::: "memory"); else asm volatile("s_waitcnt vmcnt(0)" ::: "memory"); }
;             if (pf) { PIECE(s2, ks * 3 + 0); PIECE(s2, ks * 3 + 1); PIECE(s2, ks * 3 + 2); }
;             asm volatile("s_waitcnt lgkmcnt(0)" ::: "memory");
;             BAR();
;             __builtin_amdgcn_s_setprio(1);
; #pragma unroll
;             for (int mi = 0; mi < 4; ++mi)
; #pragma unroll
;                 for (int ni = 0; ni < 4; ++ni) acc[mi][ni] = __builtin_amdgcn_mfma_f32_16x16x32_bf16(bfr[ni], af[mi], acc[mi][ni], 0, 0, 0);
;             __builtin_amdgcn_s_setprio(0);
;             BAR();
;         }
;         st = st == 2 ? 0 : st + 1;
;     }
;     if (grp == 0) BAR();
	s_sub_u32 s0, s0, 1
	s_cmp_lg_u32 s0, 0
	s_cbranch_scc1 .Lgu_kloop
	s_cmp_lg_u32 s54, 0
	s_cbranch_scc1 .Lgu_epi
	ds_read_b128 v[0:3], v188 offset:16
	ds_read_b128 v[4:7], v189 offset:16
	ds_read_b128 v[8:11], v188 offset:2064
	ds_read_b128 v[12:15], v189 offset:2064
	ds_read_b128 v[196:199], v188 offset:16400
	ds_read_b128 v[200:203], v189 offset:16400
	ds_read_b128 v[204:207], v188 offset:18448
	ds_read_b128 v[208:211], v189 offset:18448
	ds_read_b128 v[152:155], v186 offset:16
	ds_read_b128 v[156:159], v187 offset:16
	ds_read_b128 v[160:163], v186 offset:2064
	ds_read_b128 v[164:167], v187 offset:2064
	ds_read_b128 v[168:171], v186 offset:4112
	ds_read_b128 v[172:175], v187 offset:4112
	ds_read_b128 v[176:179], v186 offset:6160
	ds_read_b128 v[180:183], v187 offset:6160
	s_add_i32 m0, s39, 0xc000
	s_nop 0
	global_load_lds_dwordx4 v184, s[68:69]
	s_add_i32 m0, s39, 0xc400
	s_nop 0
	global_load_lds_dwordx4 v185, s[68:69]
	s_add_u32 s68, s68, 0x80
	s_addc_u32 s69, s69, 0
	s_waitcnt lgkmcnt(0)
	s_waitcnt vmcnt(8)
	s_barrier
	s_setprio 1
	v_mfma_f32_16x16x32_bf16 v[24:27], v[0:3], v[152:155], v[24:27]
	v_mfma_f32_16x16x32_bf16 v[28:31], v[8:11], v[152:155], v[28:31]
	v_mfma_f32_16x16x32_bf16 v[32:35], v[0:3], v[160:163], v[32:35]
	v_mfma_f32_16x16x32_bf16 v[36:39], v[8:11], v[160:163], v[36:39]
	v_mfma_f32_16x16x32_bf16 v[40:43], v[0:3], v[168:171], v[40:43]
	v_mfma_f32_16x16x32_bf16 v[44:47], v[8:11], v[168:171], v[44:47]
	v_mfma_f32_16x16x32_bf16 v[48:51], v[0:3], v[176:179], v[48:51]
	v_mfma_f32_16x16x32_bf16 v[52:55], v[8:11], v[176:179], v[52:55]
	v_mfma_f32_16x16x32_bf16 v[24:27], v[4:7], v[156:159], v[24:27]
	v_mfma_f32_16x16x32_bf16 v[28:31], v[12:15], v[156:159], v[28:31]
	v_mfma_f32_16x16x32_bf16 v[32:35], v[4:7], v[164:167], v[32:35]
	v_mfma_f32_16x16x32_bf16 v[36:39], v[12:15], v[164:167], v[36:39]
	v_mfma_f32_16x16x32_bf16 v[40:43], v[4:7], v[172:175], v[40:43]
	v_mfma_f32_16x16x32_bf16 v[44:47], v[12:15], v[172:175], v[44:47]
	v_mfma_f32_16x16x32_bf16 v[48:51], v[4:7], v[180:183], v[48:51]
	v_mfma_f32_16x16x32_bf16 v[52:55], v[12:15], v[180:183], v[52:55]
	v_mfma_f32_16x16x32_bf16 v[56:59], v[196:199], v[152:155], v[56:59]
	v_mfma_f32_16x16x32_bf16 v[60:63], v[204:207], v[152:155], v[60:63]
	v_mfma_f32_16x16x32_bf16 v[64:67], v[196:199], v[160:163], v[64:67]
	v_mfma_f32_16x16x32_bf16 v[68:71], v[204:207], v[160:163], v[68:71]
	v_mfma_f32_16x16x32_bf16 v[72:75], v[196:199], v[168:171], v[72:75]
	v_mfma_f32_16x16x32_bf16 v[76:79], v[204:207], v[168:171], v[76:79]
	v_mfma_f32_16x16x32_bf16 v[80:83], v[196:199], v[176:179], v[80:83]
	v_mfma_f32_16x16x32_bf16 v[84:87], v[204:207], v[176:179], v[84:87]
	v_mfma_f32_16x16x32_bf16 v[56:59], v[200:203], v[156:159], v[56:59]
	v_mfma_f32_16x16x32_bf16 v[60:63], v[208:211], v[156:159], v[60:63]
	v_mfma_f32_16x16x32_bf16 v[64:67], v[200:203], v[164:167], v[64:67]
	v_mfma_f32_16x16x32_bf16 v[68:71], v[208:211], v[164:167], v[68:71]
	v_mfma_f32_16x16x32_bf16 v[72:75], v[200:203], v[172:175], v[72:75]
	v_mfma_f32_16x16x32_bf16 v[76:79], v[208:211], v[172:175], v[76:79]
	v_mfma_f32_16x16x32_bf16 v[80:83], v[200:203], v[180:183], v[80:83]
	v_mfma_f32_16x16x32_bf16 v[84:87], v[208:211], v[180:183], v[84:87]
	s_setprio 0
	s_barrier
	ds_read_b128 v[152:155], v186 offset:16400
	ds_read_b128 v[156:159], v187 offset:16400
	ds_read_b128 v[160:163], v186 offset:18448
	ds_read_b128 v[164:167], v187 offset:18448
	ds_read_b128 v[168:171], v186 offset:20496
	ds_read_b128 v[172:175], v187 offset:20496
	ds_read_b128 v[176:179], v186 offset:22544
	ds_read_b128 v[180:183], v187 offset:22544
	s_waitcnt lgkmcnt(0)
	s_waitcnt vmcnt(2)
	s_barrier
	s_setprio 1
	v_mfma_f32_16x16x32_bf16 v[88:91], v[0:3], v[152:155], v[88:91]
	v_mfma_f32_16x16x32_bf16 v[92:95], v[8:11], v[152:155], v[92:95]
	v_mfma_f32_16x16x32_bf16 v[96:99], v[0:3], v[160:163], v[96:99]
	v_mfma_f32_16x16x32_bf16 v[100:103], v[8:11], v[160:163], v[100:103]
	v_mfma_f32_16x16x32_bf16 v[104:107], v[0:3], v[168:171], v[104:107]
	v_mfma_f32_16x16x32_bf16 v[108:111], v[8:11], v[168:171], v[108:111]
	v_mfma_f32_16x16x32_bf16 v[112:115], v[0:3], v[176:179], v[112:115]
	v_mfma_f32_16x16x32_bf16 v[116:119], v[8:11], v[176:179], v[116:119]
	v_mfma_f32_16x16x32_bf16 v[88:91], v[4:7], v[156:159], v[88:91]
	v_mfma_f32_16x16x32_bf16 v[92:95], v[12:15], v[156:159], v[92:95]
	v_mfma_f32_16x16x32_bf16 v[96:99], v[4:7], v[164:167], v[96:99]
	v_mfma_f32_16x16x32_bf16 v[100:103], v[12:15], v[164:167], v[100:103]
	v_mfma_f32_16x16x32_bf16 v[104:107], v[4:7], v[172:175], v[104:107]
	v_mfma_f32_16x16x32_bf16 v[108:111], v[12:15], v[172:175], v[108:111]
	v_mfma_f32_16x16x32_bf16 v[112:115], v[4:7], v[180:183], v[112:115]
	v_mfma_f32_16x16x32_bf16 v[116:119], v[12:15], v[180:183], v[116:119]
	v_mfma_f32_16x16x32_bf16 v[120:123], v[196:199], v[152:155], v[120:123]
	v_mfma_f32_16x16x32_bf16 v[124:127], v[204:207], v[152:155], v[124:127]
	v_mfma_f32_16x16x32_bf16 v[128:131], v[196:199], v[160:163], v[128:131]
	v_mfma_f32_16x16x32_bf16 v[132:135], v[204:207], v[160:163], v[132:135]
	v_mfma_f32_16x16x32_bf16 v[136:139], v[196:199], v[168:171], v[136:139]
	v_mfma_f32_16x16x32_bf16 v[140:143], v[204:207], v[168:171], v[140:143]
	v_mfma_f32_16x16x32_bf16 v[144:147], v[196:199], v[176:179], v[144:147]
	v_mfma_f32_16x16x32_bf16 v[148:151], v[204:207], v[176:179], v[148:151]
	v_mfma_f32_16x16x32_bf16 v[120:123], v[200:203], v[156:159], v[120:123]
	v_mfma_f32_16x16x32_bf16 v[124:127], v[208:211], v[156:159], v[124:127]
	v_mfma_f32_16x16x32_bf16 v[128:131], v[200:203], v[164:167], v[128:131]
	v_mfma_f32_16x16x32_bf16 v[132:135], v[208:211], v[164:167], v[132:135]
	v_mfma_f32_16x16x32_bf16 v[136:139], v[200:203], v[172:175], v[136:139]
	v_mfma_f32_16x16x32_bf16 v[140:143], v[208:211], v[172:175], v[140:143]
	v_mfma_f32_16x16x32_bf16 v[144:147], v[200:203], v[180:183], v[144:147]
	v_mfma_f32_16x16x32_bf16 v[148:151], v[208:211], v[180:183], v[148:151]
	s_setprio 0
	s_barrier
; #define LAS __attribute__((address_space(3)))
; #define BAR() { __builtin_amdgcn_sched_barrier(0); __builtin_amdgcn_s_barrier(); asm volatile("" ::: "memory"); __builtin_amdgcn_sched_barrier(0); }
; DI void gemm_stream2(const bf16_t* __restrict__ A, int lda, const bf16_t* __restrict__ Bt, int ldb, int K, int m0, int n0, ...
;     ...
; #pragma unroll
;         for (int ks = 0; ks < 2; ++ks) {
;             const unsigned fo = ks ? fo1 : fo0;
;             bf16x8 af[4], bfr[4];
; #pragma unroll
;             for (int i = 0; i < 4; ++i) { af[i] = *(const LAS bf16x8*)(base + aoff + i * 2048 + fo); bfr[i] = *(const LAS bf16x8*)(base + boff + i * 2048 + fo); }
;             if (ks == 1 && more) { if (pf) asm volatile("s_waitcnt vmcnt(3)" ::: "memory"); else asm volatile("s_waitcnt vmcnt(0)" ::: "memory"); }
;             if (pf) { PIECE(s2, ks * 3 + 0); PIECE(s2, ks * 3 + 1); PIECE(s2, ks * 3 + 2); }
;             asm volatile("s_waitcnt lgkmcnt(0)" ::: "memory");
;             BAR();
;             __builtin_amdgcn_s_setprio(1);
; #pragma unroll
;             for (int mi = 0; mi < 4; ++mi)
; #pragma unroll
;                 for (int ni = 0; ni < 4; ++ni) acc[mi][ni] = __builtin_amdgcn_mfma_f32_16x16x32_bf16(bfr[ni], af[mi], acc[mi][ni], 0, 0, 0);
;             __builtin_amdgcn_s_setprio(0);
;             BAR();
;         }
;         st = st == 2 ? 0 : st + 1;
;     }
;     if (grp == 0) BAR();
	ds_read_b128 v[0:3], v188 offset:32784
	ds_read_b128 v[4:7], v189 offset:32784
	ds_read_b128 v[8:11], v188 offset:34832
	ds_read_b128 v[12:15], v189 offset:34832
	ds_read_b128 v[196:199], v188 offset:49168
	ds_read_b128 v[200:203], v189 offset:49168
	ds_read_b128 v[204:207], v188 offset:51216
	ds_read_b128 v[208:211], v189 offset:51216
	ds_read_b128 v[152:155], v186 offset:32784
	ds_read_b128 v[156:159], v187 offset:32784
	ds_read_b128 v[160:163], v186 offset:34832
	ds_read_b128 v[164:167], v187 offset:34832
	ds_read_b128 v[168:171], v186 offset:36880
	ds_read_b128 v[172:175], v187 offset:36880
	ds_read_b128 v[176:179], v186 offset:38928
	ds_read_b128 v[180:183], v187 offset:38928
	s_waitcnt lgkmcnt(0)
	s_waitcnt vmcnt(0)
	s_barrier
	s_setprio 1
	v_mfma_f32_16x16x32_bf16 v[24:27], v[0:3], v[152:155], v[24:27]
	v_mfma_f32_16x16x32_bf16 v[28:31], v[8:11], v[152:155], v[28:31]
	v_mfma_f32_16x16x32_bf16 v[32:35], v[0:3], v[160:163], v[32:35]
	v_mfma_f32_16x16x32_bf16 v[36:39], v[8:11], v[160:163], v[36:39]
	v_mfma_f32_16x16x32_bf16 v[40:43], v[0:3], v[168:171], v[40:43]
	v_mfma_f32_16x16x32_bf16 v[44:47], v[8:11], v[168:171], v[44:47]
	v_mfma_f32_16x16x32_bf16 v[48:51], v[0:3], v[176:179], v[48:51]
	v_mfma_f32_16x16x32_bf16 v[52:55], v[8:11], v[176:179], v[52:55]
	v_mfma_f32_16x16x32_bf16 v[24:27], v[4:7], v[156:159], v[24:27]
	v_mfma_f32_16x16x32_bf16 v[28:31], v[12:15], v[156:159], v[28:31]
	v_mfma_f32_16x16x32_bf16 v[32:35], v[4:7], v[164:167], v[32:35]
	v_mfma_f32_16x16x32_bf16 v[36:39], v[12:15], v[164:167], v[36:39]
	v_mfma_f32_16x16x32_bf16 v[40:43], v[4:7], v[172:175], v[40:43]
	v_mfma_f32_16x16x32_bf16 v[44:47], v[12:15], v[172:175], v[44:47]
	v_mfma_f32_16x16x32_bf16 v[48:51], v[4:7], v[180:183], v[48:51]
	v_mfma_f32_16x16x32_bf16 v[52:55], v[12:15], v[180:183], v[52:55]
	v_mfma_f32_16x16x32_bf16 v[56:59], v[196:199], v[152:155], v[56:59]
	v_mfma_f32_16x16x32_bf16 v[60:63], v[204:207], v[152:155], v[60:63]
	v_mfma_f32_16x16x32_bf16 v[64:67], v[196:199], v[160:163], v[64:67]
	v_mfma_f32_16x16x32_bf16 v[68:71], v[204:207], v[160:163], v[68:71]
	v_mfma_f32_16x16x32_bf16 v[72:75], v[196:199], v[168:171], v[72:75]
	v_mfma_f32_16x16x32_bf16 v[76:79], v[204:207], v[168:171], v[76:79]
	v_mfma_f32_16x16x32_bf16 v[80:83], v[196:199], v[176:179], v[80:83]
	v_mfma_f32_16x16x32_bf16 v[84:87], v[204:207], v[176:179], v[84:87]
	v_mfma_f32_16x16x32_bf16 v[56:59], v[200:203], v[156:159], v[56:59]
	v_mfma_f32_16x16x32_bf16 v[60:63], v[208:211], v[156:159], v[60:63]
	v_mfma_f32_16x16x32_bf16 v[64:67], v[200:203], v[164:167], v[64:67]
	v_mfma_f32_16x16x32_bf16 v[68:71], v[208:211], v[164:167], v[68:71]
	v_mfma_f32_16x16x32_bf16 v[72:75], v[200:203], v[172:175], v[72:75]
	v_mfma_f32_16x16x32_bf16 v[76:79], v[208:211], v[172:175], v[76:79]
	v_mfma_f32_16x16x32_bf16 v[80:83], v[200:203], v[180:183], v[80:83]
	v_mfma_f32_16x16x32_bf16 v[84:87], v[208:211], v[180:183], v[84:87]
	s_setprio 0
	s_barrier
	ds_read_b128 v[152:155], v186 offset:49168
	ds_read_b128 v[156:159], v187 offset:49168
	ds_read_b128 v[160:163], v186 offset:51216
	ds_read_b128 v[164:167], v187 offset:51216
	ds_read_b128 v[168:171], v186 offset:53264
	ds_read_b128 v[172:175], v187 offset:53264
	ds_read_b128 v[176:179], v186 offset:55312
	ds_read_b128 v[180:183], v187 offset:55312
	s_waitcnt lgkmcnt(0)
	s_barrier
	s_setprio 1
	v_mfma_f32_16x16x32_bf16 v[88:91], v[0:3], v[152:155], v[88:91]
	v_mfma_f32_16x16x32_bf16 v[92:95], v[8:11], v[152:155], v[92:95]
	v_mfma_f32_16x16x32_bf16 v[96:99], v[0:3], v[160:163], v[96:99]
	v_mfma_f32_16x16x32_bf16 v[100:103], v[8:11], v[160:163], v[100:103]
	v_mfma_f32_16x16x32_bf16 v[104:107], v[0:3], v[168:171], v[104:107]
	v_mfma_f32_16x16x32_bf16 v[108:111], v[8:11], v[168:171], v[108:111]
	v_mfma_f32_16x16x32_bf16 v[112:115], v[0:3], v[176:179], v[112:115]
	v_mfma_f32_16x16x32_bf16 v[116:119], v[8:11], v[176:179], v[116:119]
	v_mfma_f32_16x16x32_bf16 v[88:91], v[4:7], v[156:159], v[88:91]
	v_mfma_f32_16x16x32_bf16 v[92:95], v[12:15], v[156:159], v[92:95]
	v_mfma_f32_16x16x32_bf16 v[96:99], v[4:7], v[164:167], v[96:99]
	v_mfma_f32_16x16x32_bf16 v[100:103], v[12:15], v[164:167], v[100:103]
	v_mfma_f32_16x16x32_bf16 v[104:107], v[4:7], v[172:175], v[104:107]
	v_mfma_f32_16x16x32_bf16 v[108:111], v[12:15], v[172:175], v[108:111]
	v_mfma_f32_16x16x32_bf16 v[112:115], v[4:7], v[180:183], v[112:115]
	v_mfma_f32_16x16x32_bf16 v[116:119], v[12:15], v[180:183], v[116:119]
	v_mfma_f32_16x16x32_bf16 v[120:123], v[196:199], v[152:155], v[120:123]
	v_mfma_f32_16x16x32_bf16 v[124:127], v[204:207], v[152:155], v[124:127]
	v_mfma_f32_16x16x32_bf16 v[128:131], v[196:199], v[160:163], v[128:131]
	v_mfma_f32_16x16x32_bf16 v[132:135], v[204:207], v[160:163], v[132:135]
	v_mfma_f32_16x16x32_bf16 v[136:139], v[196:199], v[168:171], v[136:139]
	v_mfma_f32_16x16x32_bf16 v[140:143], v[204:207], v[168:171], v[140:143]
	v_mfma_f32_16x16x32_bf16 v[144:147], v[196:199], v[176:179], v[144:147]
	v_mfma_f32_16x16x32_bf16 v[148:151], v[204:207], v[176:179], v[148:151]
	v_mfma_f32_16x16x32_bf16 v[120:123], v[200:203], v[156:159], v[120:123]
	v_mfma_f32_16x16x32_bf16 v[124:127], v[208:211], v[156:159], v[124:127]
	v_mfma_f32_16x16x32_bf16 v[128:131], v[200:203], v[164:167], v[128:131]
	v_mfma_f32_16x16x32_bf16 v[132:135], v[208:211], v[164:167], v[132:135]
	v_mfma_f32_16x16x32_bf16 v[136:139], v[200:203], v[172:175], v[136:139]
	v_mfma_f32_16x16x32_bf16 v[140:143], v[208:211], v[172:175], v[140:143]
	v_mfma_f32_16x16x32_bf16 v[144:147], v[200:203], v[180:183], v[144:147]
	v_mfma_f32_16x16x32_bf16 v[148:151], v[208:211], v[180:183], v[148:151]
	s_setprio 0
	s_barrier
	s_cmp_lg_u32 s33, 0
	s_cbranch_scc1 .Lgu_epi
	s_barrier
	.p2alignl 6, 3212836864
	s_nop 0
